# MoBA loop back-edge rotation: per-step barrier moved behind the scalar next-step scan
# speedup vs baseline: 1.0076x; 1.0030x over previous
.LBB0_139:
	s_add_i32 s10, s14, 1
	s_mov_b32 s16, s14
	s_cmp_ge_i32 s10, s48
	s_mov_b64 s[0:1], 0
	s_cbranch_scc1 .LBB0_147
	s_lshl_b32 s0, s16, 7
	s_add_i32 s11, s13, s0
	s_branch .LBB0_142

.LBB0_148:
	s_waitcnt lgkmcnt(0)
	s_barrier
	s_cmp_ge_i32 s16, s48
	s_cselect_b64 s[8:9], -1, 0
	s_mov_b64 s[80:81], s[0:1]
	s_and_b64 vcc, exec, s[8:9]
	s_cbranch_vccnz .LBB0_151
	s_ashr_i32 s82, s51, 1
	s_sub_i32 s82, s47, s82
	s_lshl_b32 s82, 1, s82
	s_and_b32 s82, s82, s49
	s_cmp_lg_u32 s82, 0
	s_cbranch_scc1 .LBB0_151
	s_xor_b32 s10, s15, 1
	s_mul_i32 s10, s10, 0x11000
	s_add_i32 s10, s10, 0
	v_add3_u32 v85, s10, v165, v216
	v_add3_u32 v84, s10, v0, v216
	v_add_u32_e32 v86, 0x8800, v85
	s_waitcnt vmcnt(7)
	ds_write_b128 v84, v[4:7]
	s_waitcnt vmcnt(6)
	ds_write2_b64 v86, v[8:9], v[10:11] offset1:2
	s_waitcnt vmcnt(5)
	ds_write_b128 v84, v[12:15] offset:8704
	v_add_u32_e32 v86, 0xa800, v85
	s_waitcnt vmcnt(4)
	ds_write2_b64 v86, v[16:17], v[18:19] offset0:64 offset1:66
	s_waitcnt vmcnt(3)
	ds_write_b128 v84, v[20:23] offset:17408
	v_add_u32_e32 v86, 0xc800, v85
	s_waitcnt vmcnt(2)
	ds_write2_b64 v86, v[24:25], v[26:27] offset0:128 offset1:130
	s_waitcnt vmcnt(1)
	ds_write_b128 v84, v[28:31] offset:26112
	v_add_u32_e32 v84, 0xe800, v85
	s_andn2_b64 vcc, exec, s[0:1]
	s_waitcnt vmcnt(0)
	ds_write2_b64 v84, v[32:33], v[34:35] offset0:192 offset1:194
	s_cbranch_vccnz .LBB0_151
	s_lshr_b32 s0, s14, 1
	s_sub_i32 s0, s47, s0
	s_lshl_b32 s1, s14, 7
	s_lshl_b32 s0, s0, 8
	s_and_b32 s1, s1, 0x80
	s_or_b32 s0, s0, s1
	s_ashr_i32 s1, s0, 31
	v_lshl_add_u64 v[4:5], v[140:141], 0, s[0:1]
	v_mov_b64_e32 v[6:7], s[88:89]
	v_lshl_add_u64 v[28:29], s[0:1], 1, v[118:119]
	v_mad_u64_u32 v[6:7], s[0:1], v4, s72, v[6:7]
	v_mad_i32_i24 v7, v5, s72, v7
	v_lshl_add_u64 v[4:5], v[6:7], 0, s[20:21]
	v_lshl_add_u64 v[30:31], v[4:5], 0, v[2:3]
	v_add_co_u32_e32 v4, vcc, s3, v30
	s_mov_b32 s0, 0x3d000
	s_nop 0
	v_addc_co_u32_e32 v5, vcc, 0, v31, vcc
	v_add_co_u32_e32 v12, vcc, s0, v30
	v_lshl_add_u64 v[8:9], v[28:29], 0, v[146:147]
	s_nop 0
	v_addc_co_u32_e32 v13, vcc, 0, v31, vcc
	v_add_co_u32_e32 v20, vcc, 0x79000, v30
	v_lshl_add_u64 v[16:17], v[28:29], 0, v[148:149]
	s_nop 0
	v_addc_co_u32_e32 v21, vcc, 0, v31, vcc
	v_add_co_u32_e32 v30, vcc, 0xb5000, v30
	v_lshl_add_u64 v[24:25], v[28:29], 0, v[150:151]
	s_nop 0
	v_addc_co_u32_e32 v31, vcc, 0, v31, vcc
	v_lshl_add_u64 v[32:33], v[28:29], 0, v[152:153]
	global_load_dwordx4 v[4:7], v[4:5], off offset:1024
	s_nop 0
	global_load_dwordx4 v[8:11], v[8:9], off
	s_nop 0
	global_load_dwordx4 v[12:15], v[12:13], off offset:1024
	s_nop 0
	global_load_dwordx4 v[16:19], v[16:17], off
	s_nop 0
	global_load_dwordx4 v[20:23], v[20:21], off offset:1024
	s_nop 0
	global_load_dwordx4 v[24:27], v[24:25], off
	s_nop 0
	global_load_dwordx4 v[28:31], v[30:31], off offset:1024
	s_nop 0
	global_load_dwordx4 v[32:35], v[32:33], off
